# prologue x_half loop hand-pipelined: 4 K-steps of loads in flight with counted vmcnt instead of load-wait-use per element group
# speedup vs baseline: 1.0172x; 1.0172x over previous
; __device__ __forceinline__ unsigned cvt_pk_bf16(float lo, float hi) { unsigned r; asm volatile("v_cvt_pk_bf16_f32 %0, %1, %2" : "=v"(r) : "v"(lo), "v"(hi)); return r; }
; __device__ __forceinline__ void x_half(KA a, int grp, int half, int lane, f32x4& acc, float& ss) {
;     ...
;     const int row0 = grp * 16, r = lane & 15, quad = lane >> 4, kbase = half * 1024;
;     const float* xr = x + (size_t)(row0 + r) * D_ + quad * 8 + kbase; bf16_t* br = XB + (size_t)(row0 + r) * D_ + quad * 8 + kbase;
;     const float* wp = W + (size_t)(kbase + quad * 8) * 6160 + 6144 + r; const float* gp = gmix + kbase + quad * 8;
;     acc = (f32x4){0.f, 0.f, 0.f, 0.f}; ss = 0.f;
; #pragma unroll 4
;     for (int k0 = 0; k0 < 1024; k0 += 32) {
;         const f32x4 a0 = *(const f32x4*)(xr + k0), a1 = *(const f32x4*)(xr + k0 + 4);
;         ss += (a0[0] * a0[0] + a0[1] * a0[1]) + (a0[2] * a0[2] + a0[3] * a0[3]) + (a1[0] * a1[0] + a1[1] * a1[1]) + (a1[2] * a1[2] + a1[3] * a1[3]);
;         u32x4 aw; aw.x = cvt_pk_bf16(a0[0], a0[1]); aw.y = cvt_pk_bf16(a0[2], a0[3]); aw.z = cvt_pk_bf16(a1[0], a1[1]); aw.w = cvt_pk_bf16(a1[2], a1[3]);
;         *(u32x4*)(br + k0) = aw;
;         const f32x4 g0 = *(const f32x4*)(gp + k0), g1 = *(const f32x4*)(gp + k0 + 4);
;         const float* w = wp + (size_t)k0 * 6160;
;         u32x4 bw; bw.x = cvt_pk_bf16(w[0] * g0[0], w[6160] * g0[1]); bw.y = cvt_pk_bf16(w[2 * 6160] * g0[2], w[3 * 6160] * g0[3]);
;         bw.z = cvt_pk_bf16(w[4 * 6160] * g1[0], w[5 * 6160] * g1[1]); bw.w = cvt_pk_bf16(w[6 * 6160] * g1[2], w[7 * 6160] * g1[3]);
;         acc = __builtin_amdgcn_mfma_f32_16x16x32_bf16(__builtin_bit_cast(bf16x8, aw), __builtin_bit_cast(bf16x8, bw), acc, 0, 0, 0);
;     }
.LBB0_9:
	v_ashrrev_i32_e32 v67, 31, v66
	v_lshlrev_b64 v[4:5], 13, v[66:67]
	v_lshlrev_b64 v[6:7], 12, v[66:67]
	v_lshl_add_u64 v[4:5], s[8:9], 0, v[4:5]
	v_lshl_add_u64 v[70:71], v[68:69], 0, v[6:7]
	s_movk_i32 s71, 0xffe0
	s_mov_b64 s[26:27], s[10:11]
	v_mov_b64_e32 v[72:73], v[62:63]
	v_mov_b32_e32 v2, 0
	v_mov_b32_e32 v6, 0
	v_mov_b32_e32 v7, v3
	v_mov_b32_e32 v8, v3
	v_mov_b32_e32 v9, v3
	s_load_dwordx2 s[28:29], s[92:93], 0x20
	v_lshl_add_u64 v[4:5], v[4:5], 0, v[64:65]
	v_lshrrev_b32_e32 v26, 4, v167
	v_mul_u32_u24_e32 v26, 0x30200, v26
	v_lshl_add_u32 v26, v79, 2, v26
	v_add_u32_e32 v27, 0x6040, v26
	v_add_u32_e32 v28, 0xc080, v26
	v_add_u32_e32 v29, 0x120c0, v26
	v_add_u32_e32 v30, 0x18100, v26
	v_add_u32_e32 v31, 0x1e140, v26
	v_add_u32_e32 v32, 0x24180, v26
	v_add_u32_e32 v33, 0x2a1c0, v26
	s_lshr_b32 s25, s46, 2
	s_mul_i32 s25, s25, 0x1810000
	s_add_i32 s25, s25, 0x6000
	s_waitcnt vmcnt(0) lgkmcnt(0)
	s_add_u32 s28, s28, s25
	s_addc_u32 s29, s29, 0
	global_load_dwordx4 v[100:103], v[4:5], off
	global_load_dwordx4 v[104:107], v[4:5], off offset:16
	global_load_dwordx4 v[108:111], v64, s[26:27]
	global_load_dwordx4 v[112:115], v64, s[26:27] offset:16
	global_load_dword v116, v26, s[28:29]
	global_load_dword v117, v27, s[28:29]
	global_load_dword v118, v28, s[28:29]
	global_load_dword v119, v29, s[28:29]
	global_load_dword v120, v30, s[28:29]
	global_load_dword v121, v31, s[28:29]
	global_load_dword v122, v32, s[28:29]
	global_load_dword v123, v33, s[28:29]
	s_add_u32 s28, s28, 0xc0800
	s_addc_u32 s29, s29, 0
	global_load_dwordx4 v[124:127], v[4:5], off offset:128
	global_load_dwordx4 v[128:131], v[4:5], off offset:144
	global_load_dwordx4 v[132:135], v64, s[26:27] offset:128
	global_load_dwordx4 v[136:139], v64, s[26:27] offset:144
	global_load_dword v140, v26, s[28:29]
	global_load_dword v141, v27, s[28:29]
	global_load_dword v142, v28, s[28:29]
	global_load_dword v143, v29, s[28:29]
	global_load_dword v144, v30, s[28:29]
	global_load_dword v145, v31, s[28:29]
	global_load_dword v146, v32, s[28:29]
	global_load_dword v147, v33, s[28:29]
	s_add_u32 s28, s28, 0xc0800
	s_addc_u32 s29, s29, 0
	global_load_dwordx4 v[168:171], v[4:5], off offset:256
	global_load_dwordx4 v[172:175], v[4:5], off offset:272
	global_load_dwordx4 v[176:179], v64, s[26:27] offset:256
	global_load_dwordx4 v[180:183], v64, s[26:27] offset:272
	global_load_dword v184, v26, s[28:29]
	global_load_dword v185, v27, s[28:29]
	global_load_dword v186, v28, s[28:29]
	global_load_dword v187, v29, s[28:29]
	global_load_dword v188, v30, s[28:29]
	global_load_dword v189, v31, s[28:29]
	global_load_dword v190, v32, s[28:29]
	global_load_dword v191, v33, s[28:29]
	s_add_u32 s28, s28, 0xc0800
	s_addc_u32 s29, s29, 0
	global_load_dwordx4 v[192:195], v[4:5], off offset:384
	global_load_dwordx4 v[196:199], v[4:5], off offset:400
	global_load_dwordx4 v[200:203], v64, s[26:27] offset:384
	global_load_dwordx4 v[204:207], v64, s[26:27] offset:400
	global_load_dword v208, v26, s[28:29]
	global_load_dword v209, v27, s[28:29]
	global_load_dword v210, v28, s[28:29]
	global_load_dword v211, v29, s[28:29]
	global_load_dword v212, v30, s[28:29]
	global_load_dword v213, v31, s[28:29]
	global_load_dword v214, v32, s[28:29]
	global_load_dword v215, v33, s[28:29]
	s_add_u32 s28, s28, 0xc0800
	s_addc_u32 s29, s29, 0
	s_mov_b32 s71, 7
.Lxh_loop:
	s_waitcnt vmcnt(36)
	v_cvt_pk_bf16_f32 v10, v100, v101
	v_cvt_pk_bf16_f32 v11, v102, v103
	v_cvt_pk_bf16_f32 v12, v104, v105
	v_cvt_pk_bf16_f32 v13, v106, v107
	global_store_dwordx4 v[70:71], v[10:13], off offset:-128
	v_mul_f32_e32 v116, v116, v108
	v_mul_f32_e32 v117, v117, v109
	v_mul_f32_e32 v118, v118, v110
	v_mul_f32_e32 v119, v119, v111
	v_mul_f32_e32 v120, v120, v112
	v_mul_f32_e32 v121, v121, v113
	v_mul_f32_e32 v122, v122, v114
	v_mul_f32_e32 v123, v123, v115
	v_cvt_pk_bf16_f32 v14, v116, v117
	v_cvt_pk_bf16_f32 v15, v118, v119
	v_cvt_pk_bf16_f32 v16, v120, v121
	v_cvt_pk_bf16_f32 v17, v122, v123
	v_mul_f32_e32 v100, v100, v100
	v_mul_f32_e32 v101, v101, v101
	v_mul_f32_e32 v102, v102, v102
	v_mul_f32_e32 v103, v103, v103
	v_mul_f32_e32 v104, v104, v104
	v_mul_f32_e32 v105, v105, v105
	v_mul_f32_e32 v106, v106, v106
	v_mul_f32_e32 v107, v107, v107
	v_add_f32_e32 v100, v100, v101
	v_add_f32_e32 v102, v102, v103
	v_add_f32_e32 v100, v100, v102
	v_add_f32_e32 v104, v104, v105
	v_add_f32_e32 v100, v100, v104
	v_add_f32_e32 v106, v106, v107
	v_add_f32_e32 v100, v100, v106
	v_add_f32_e32 v2, v2, v100
	v_mfma_f32_16x16x32_bf16 v[6:9], v[10:13], v[14:17], v[6:9]
	global_load_dwordx4 v[100:103], v[4:5], off offset:512
	global_load_dwordx4 v[104:107], v[4:5], off offset:528
	global_load_dwordx4 v[108:111], v64, s[26:27] offset:512
	global_load_dwordx4 v[112:115], v64, s[26:27] offset:528
	global_load_dword v116, v26, s[28:29]
	global_load_dword v117, v27, s[28:29]
	global_load_dword v118, v28, s[28:29]
	global_load_dword v119, v29, s[28:29]
	global_load_dword v120, v30, s[28:29]
	global_load_dword v121, v31, s[28:29]
	global_load_dword v122, v32, s[28:29]
	global_load_dword v123, v33, s[28:29]
	s_add_u32 s28, s28, 0xc0800
	s_addc_u32 s29, s29, 0
	s_waitcnt vmcnt(36)
; __device__ __forceinline__ unsigned cvt_pk_bf16(float lo, float hi) { unsigned r; asm volatile("v_cvt_pk_bf16_f32 %0, %1, %2" : "=v"(r) : "v"(lo), "v"(hi)); return r; }
; __device__ __forceinline__ void x_half(KA a, int grp, int half, int lane, f32x4& acc, float& ss) {
;     ...
;     const int row0 = grp * 16, r = lane & 15, quad = lane >> 4, kbase = half * 1024;
;     const float* xr = x + (size_t)(row0 + r) * D_ + quad * 8 + kbase; bf16_t* br = XB + (size_t)(row0 + r) * D_ + quad * 8 + kbase;
;     const float* wp = W + (size_t)(kbase + quad * 8) * 6160 + 6144 + r; const float* gp = gmix + kbase + quad * 8;
;     acc = (f32x4){0.f, 0.f, 0.f, 0.f}; ss = 0.f;
; #pragma unroll 4
;     for (int k0 = 0; k0 < 1024; k0 += 32) {
;         const f32x4 a0 = *(const f32x4*)(xr + k0), a1 = *(const f32x4*)(xr + k0 + 4);
;         ss += (a0[0] * a0[0] + a0[1] * a0[1]) + (a0[2] * a0[2] + a0[3] * a0[3]) + (a1[0] * a1[0] + a1[1] * a1[1]) + (a1[2] * a1[2] + a1[3] * a1[3]);
;         u32x4 aw; aw.x = cvt_pk_bf16(a0[0], a0[1]); aw.y = cvt_pk_bf16(a0[2], a0[3]); aw.z = cvt_pk_bf16(a1[0], a1[1]); aw.w = cvt_pk_bf16(a1[2], a1[3]);
;         *(u32x4*)(br + k0) = aw;
;         const f32x4 g0 = *(const f32x4*)(gp + k0), g1 = *(const f32x4*)(gp + k0 + 4);
;         const float* w = wp + (size_t)k0 * 6160;
;         u32x4 bw; bw.x = cvt_pk_bf16(w[0] * g0[0], w[6160] * g0[1]); bw.y = cvt_pk_bf16(w[2 * 6160] * g0[2], w[3 * 6160] * g0[3]);
;         bw.z = cvt_pk_bf16(w[4 * 6160] * g1[0], w[5 * 6160] * g1[1]); bw.w = cvt_pk_bf16(w[6 * 6160] * g1[2], w[7 * 6160] * g1[3]);
;         acc = __builtin_amdgcn_mfma_f32_16x16x32_bf16(__builtin_bit_cast(bf16x8, aw), __builtin_bit_cast(bf16x8, bw), acc, 0, 0, 0);
;     }
	v_cvt_pk_bf16_f32 v18, v124, v125
	v_cvt_pk_bf16_f32 v19, v126, v127
	v_cvt_pk_bf16_f32 v20, v128, v129
	v_cvt_pk_bf16_f32 v21, v130, v131
	global_store_dwordx4 v[70:71], v[18:21], off offset:-64
	v_mul_f32_e32 v140, v140, v132
	v_mul_f32_e32 v141, v141, v133
	v_mul_f32_e32 v142, v142, v134
	v_mul_f32_e32 v143, v143, v135
	v_mul_f32_e32 v144, v144, v136
	v_mul_f32_e32 v145, v145, v137
	v_mul_f32_e32 v146, v146, v138
	v_mul_f32_e32 v147, v147, v139
	v_cvt_pk_bf16_f32 v22, v140, v141
	v_cvt_pk_bf16_f32 v23, v142, v143
	v_cvt_pk_bf16_f32 v24, v144, v145
	v_cvt_pk_bf16_f32 v25, v146, v147
	v_mul_f32_e32 v124, v124, v124
	v_mul_f32_e32 v125, v125, v125
	v_mul_f32_e32 v126, v126, v126
	v_mul_f32_e32 v127, v127, v127
	v_mul_f32_e32 v128, v128, v128
	v_mul_f32_e32 v129, v129, v129
	v_mul_f32_e32 v130, v130, v130
	v_mul_f32_e32 v131, v131, v131
	v_add_f32_e32 v124, v124, v125
	v_add_f32_e32 v126, v126, v127
	v_add_f32_e32 v124, v124, v126
	v_add_f32_e32 v128, v128, v129
	v_add_f32_e32 v124, v124, v128
	v_add_f32_e32 v130, v130, v131
	v_add_f32_e32 v124, v124, v130
	v_add_f32_e32 v2, v2, v124
	v_mfma_f32_16x16x32_bf16 v[6:9], v[18:21], v[22:25], v[6:9]
	global_load_dwordx4 v[124:127], v[4:5], off offset:640
	global_load_dwordx4 v[128:131], v[4:5], off offset:656
	global_load_dwordx4 v[132:135], v64, s[26:27] offset:640
	global_load_dwordx4 v[136:139], v64, s[26:27] offset:656
	global_load_dword v140, v26, s[28:29]
	global_load_dword v141, v27, s[28:29]
	global_load_dword v142, v28, s[28:29]
	global_load_dword v143, v29, s[28:29]
	global_load_dword v144, v30, s[28:29]
	global_load_dword v145, v31, s[28:29]
	global_load_dword v146, v32, s[28:29]
	global_load_dword v147, v33, s[28:29]
	s_add_u32 s28, s28, 0xc0800
	s_addc_u32 s29, s29, 0
	s_waitcnt vmcnt(36)
	v_cvt_pk_bf16_f32 v10, v168, v169
	v_cvt_pk_bf16_f32 v11, v170, v171
	v_cvt_pk_bf16_f32 v12, v172, v173
	v_cvt_pk_bf16_f32 v13, v174, v175
	global_store_dwordx4 v[70:71], v[10:13], off
	v_mul_f32_e32 v184, v184, v176
	v_mul_f32_e32 v185, v185, v177
	v_mul_f32_e32 v186, v186, v178
	v_mul_f32_e32 v187, v187, v179
	v_mul_f32_e32 v188, v188, v180
	v_mul_f32_e32 v189, v189, v181
	v_mul_f32_e32 v190, v190, v182
	v_mul_f32_e32 v191, v191, v183
	v_cvt_pk_bf16_f32 v14, v184, v185
	v_cvt_pk_bf16_f32 v15, v186, v187
	v_cvt_pk_bf16_f32 v16, v188, v189
	v_cvt_pk_bf16_f32 v17, v190, v191
	v_mul_f32_e32 v168, v168, v168
	v_mul_f32_e32 v169, v169, v169
	v_mul_f32_e32 v170, v170, v170
	v_mul_f32_e32 v171, v171, v171
	v_mul_f32_e32 v172, v172, v172
	v_mul_f32_e32 v173, v173, v173
	v_mul_f32_e32 v174, v174, v174
	v_mul_f32_e32 v175, v175, v175
	v_add_f32_e32 v168, v168, v169
	v_add_f32_e32 v170, v170, v171
	v_add_f32_e32 v168, v168, v170
	v_add_f32_e32 v172, v172, v173
	v_add_f32_e32 v168, v168, v172
	v_add_f32_e32 v174, v174, v175
	v_add_f32_e32 v168, v168, v174
	v_add_f32_e32 v2, v2, v168
	v_mfma_f32_16x16x32_bf16 v[6:9], v[10:13], v[14:17], v[6:9]
	global_load_dwordx4 v[168:171], v[4:5], off offset:768
	global_load_dwordx4 v[172:175], v[4:5], off offset:784
	global_load_dwordx4 v[176:179], v64, s[26:27] offset:768
	global_load_dwordx4 v[180:183], v64, s[26:27] offset:784
	global_load_dword v184, v26, s[28:29]
	global_load_dword v185, v27, s[28:29]
	global_load_dword v186, v28, s[28:29]
	global_load_dword v187, v29, s[28:29]
	global_load_dword v188, v30, s[28:29]
	global_load_dword v189, v31, s[28:29]
	global_load_dword v190, v32, s[28:29]
	global_load_dword v191, v33, s[28:29]
	s_add_u32 s28, s28, 0xc0800
	s_addc_u32 s29, s29, 0
	s_waitcnt vmcnt(36)
	v_cvt_pk_bf16_f32 v18, v192, v193
	v_cvt_pk_bf16_f32 v19, v194, v195
	v_cvt_pk_bf16_f32 v20, v196, v197
	v_cvt_pk_bf16_f32 v21, v198, v199
	global_store_dwordx4 v[70:71], v[18:21], off offset:64
	v_mul_f32_e32 v208, v208, v200
	v_mul_f32_e32 v209, v209, v201
	v_mul_f32_e32 v210, v210, v202
	v_mul_f32_e32 v211, v211, v203
	v_mul_f32_e32 v212, v212, v204
	v_mul_f32_e32 v213, v213, v205
	v_mul_f32_e32 v214, v214, v206
	v_mul_f32_e32 v215, v215, v207
	v_cvt_pk_bf16_f32 v22, v208, v209
	v_cvt_pk_bf16_f32 v23, v210, v211
	v_cvt_pk_bf16_f32 v24, v212, v213
	v_cvt_pk_bf16_f32 v25, v214, v215
	v_mul_f32_e32 v192, v192, v192
	v_mul_f32_e32 v193, v193, v193
	v_mul_f32_e32 v194, v194, v194
	v_mul_f32_e32 v195, v195, v195
	v_mul_f32_e32 v196, v196, v196
	v_mul_f32_e32 v197, v197, v197
	v_mul_f32_e32 v198, v198, v198
	v_mul_f32_e32 v199, v199, v199
	v_add_f32_e32 v192, v192, v193
	v_add_f32_e32 v194, v194, v195
	v_add_f32_e32 v192, v192, v194
	v_add_f32_e32 v196, v196, v197
	v_add_f32_e32 v192, v192, v196
	v_add_f32_e32 v198, v198, v199
	v_add_f32_e32 v192, v192, v198
	v_add_f32_e32 v2, v2, v192
	v_mfma_f32_16x16x32_bf16 v[6:9], v[18:21], v[22:25], v[6:9]
	global_load_dwordx4 v[192:195], v[4:5], off offset:896
	global_load_dwordx4 v[196:199], v[4:5], off offset:912
	global_load_dwordx4 v[200:203], v64, s[26:27] offset:896
	global_load_dwordx4 v[204:207], v64, s[26:27] offset:912
	global_load_dword v208, v26, s[28:29]
	global_load_dword v209, v27, s[28:29]
	global_load_dword v210, v28, s[28:29]
	global_load_dword v211, v29, s[28:29]
	global_load_dword v212, v30, s[28:29]
	global_load_dword v213, v31, s[28:29]
	global_load_dword v214, v32, s[28:29]
	global_load_dword v215, v33, s[28:29]
	s_add_u32 s28, s28, 0xc0800
	s_addc_u32 s29, s29, 0
	v_lshl_add_u64 v[4:5], v[4:5], 0, s[14:15]
	s_add_u32 s26, s26, 0x200
	s_addc_u32 s27, s27, 0
	v_lshl_add_u64 v[70:71], v[70:71], 0, s[22:23]
	s_sub_i32 s71, s71, 1
	s_cmp_lg_u32 s71, 0
	s_cbranch_scc1 .Lxh_loop
; __device__ __forceinline__ unsigned cvt_pk_bf16(float lo, float hi) { unsigned r; asm volatile("v_cvt_pk_bf16_f32 %0, %1, %2" : "=v"(r) : "v"(lo), "v"(hi)); return r; }
; #define LAS __attribute__((address_space(3)))
; __device__ __forceinline__ void x_half(KA a, int grp, int half, int lane, f32x4& acc, float& ss) {
;     ...
;     for (int k0 = 0; k0 < 1024; k0 += 32) {
;         const f32x4 a0 = *(const f32x4*)(xr + k0), a1 = *(const f32x4*)(xr + k0 + 4);
;         ss += (a0[0] * a0[0] + a0[1] * a0[1]) + (a0[2] * a0[2] + a0[3] * a0[3]) + (a1[0] * a1[0] + a1[1] * a1[1]) + (a1[2] * a1[2] + a1[3] * a1[3]);
;         u32x4 aw; aw.x = cvt_pk_bf16(a0[0], a0[1]); aw.y = cvt_pk_bf16(a0[2], a0[3]); aw.z = cvt_pk_bf16(a1[0], a1[1]); aw.w = cvt_pk_bf16(a1[2], a1[3]);
;         *(u32x4*)(br + k0) = aw;
;         const f32x4 g0 = *(const f32x4*)(gp + k0), g1 = *(const f32x4*)(gp + k0 + 4);
;         const float* w = wp + (size_t)k0 * 6160;
;         u32x4 bw; bw.x = cvt_pk_bf16(w[0] * g0[0], w[6160] * g0[1]); bw.y = cvt_pk_bf16(w[2 * 6160] * g0[2], w[3 * 6160] * g0[3]);
;         bw.z = cvt_pk_bf16(w[4 * 6160] * g1[0], w[5 * 6160] * g1[1]); bw.w = cvt_pk_bf16(w[6 * 6160] * g1[2], w[7 * 6160] * g1[3]);
;         acc = __builtin_amdgcn_mfma_f32_16x16x32_bf16(__builtin_bit_cast(bf16x8, aw), __builtin_bit_cast(bf16x8, bw), acc, 0, 0, 0);
;     }
; __device__ __forceinline__ void prologue(KA a, LAS unsigned char* lds, int bid, int G, int lane, int wave) {
;     ...
;         LAS float* xs = (LAS float*)(lds + (wave & 3) * 16384 + 12288) + lane * 5;
;         if (wave >= 4) { xs[0] = acc[0]; xs[1] = acc[1]; xs[2] = acc[2]; xs[3] = acc[3]; xs[4] = ss; }
	s_waitcnt vmcnt(36)
	v_cvt_pk_bf16_f32 v10, v100, v101
	v_cvt_pk_bf16_f32 v11, v102, v103
	v_cvt_pk_bf16_f32 v12, v104, v105
	v_cvt_pk_bf16_f32 v13, v106, v107
	global_store_dwordx4 v[70:71], v[10:13], off offset:-128
	v_mul_f32_e32 v116, v116, v108
	v_mul_f32_e32 v117, v117, v109
	v_mul_f32_e32 v118, v118, v110
	v_mul_f32_e32 v119, v119, v111
	v_mul_f32_e32 v120, v120, v112
	v_mul_f32_e32 v121, v121, v113
	v_mul_f32_e32 v122, v122, v114
	v_mul_f32_e32 v123, v123, v115
	v_cvt_pk_bf16_f32 v14, v116, v117
	v_cvt_pk_bf16_f32 v15, v118, v119
	v_cvt_pk_bf16_f32 v16, v120, v121
	v_cvt_pk_bf16_f32 v17, v122, v123
	v_mul_f32_e32 v100, v100, v100
	v_mul_f32_e32 v101, v101, v101
	v_mul_f32_e32 v102, v102, v102
	v_mul_f32_e32 v103, v103, v103
	v_mul_f32_e32 v104, v104, v104
	v_mul_f32_e32 v105, v105, v105
	v_mul_f32_e32 v106, v106, v106
	v_mul_f32_e32 v107, v107, v107
	v_add_f32_e32 v100, v100, v101
	v_add_f32_e32 v102, v102, v103
	v_add_f32_e32 v100, v100, v102
	v_add_f32_e32 v104, v104, v105
	v_add_f32_e32 v100, v100, v104
	v_add_f32_e32 v106, v106, v107
	v_add_f32_e32 v100, v100, v106
	v_add_f32_e32 v2, v2, v100
	v_mfma_f32_16x16x32_bf16 v[6:9], v[10:13], v[14:17], v[6:9]
	s_waitcnt vmcnt(24)
	v_cvt_pk_bf16_f32 v18, v124, v125
	v_cvt_pk_bf16_f32 v19, v126, v127
	v_cvt_pk_bf16_f32 v20, v128, v129
	v_cvt_pk_bf16_f32 v21, v130, v131
	global_store_dwordx4 v[70:71], v[18:21], off offset:-64
	v_mul_f32_e32 v140, v140, v132
	v_mul_f32_e32 v141, v141, v133
	v_mul_f32_e32 v142, v142, v134
	v_mul_f32_e32 v143, v143, v135
	v_mul_f32_e32 v144, v144, v136
	v_mul_f32_e32 v145, v145, v137
	v_mul_f32_e32 v146, v146, v138
	v_mul_f32_e32 v147, v147, v139
	v_cvt_pk_bf16_f32 v22, v140, v141
	v_cvt_pk_bf16_f32 v23, v142, v143
	v_cvt_pk_bf16_f32 v24, v144, v145
	v_cvt_pk_bf16_f32 v25, v146, v147
	v_mul_f32_e32 v124, v124, v124
	v_mul_f32_e32 v125, v125, v125
	v_mul_f32_e32 v126, v126, v126
	v_mul_f32_e32 v127, v127, v127
	v_mul_f32_e32 v128, v128, v128
	v_mul_f32_e32 v129, v129, v129
	v_mul_f32_e32 v130, v130, v130
	v_mul_f32_e32 v131, v131, v131
	v_add_f32_e32 v124, v124, v125
	v_add_f32_e32 v126, v126, v127
	v_add_f32_e32 v124, v124, v126
	v_add_f32_e32 v128, v128, v129
	v_add_f32_e32 v124, v124, v128
	v_add_f32_e32 v130, v130, v131
	v_add_f32_e32 v124, v124, v130
	v_add_f32_e32 v2, v2, v124
	v_mfma_f32_16x16x32_bf16 v[6:9], v[18:21], v[22:25], v[6:9]
	s_waitcnt vmcnt(12)
	v_cvt_pk_bf16_f32 v10, v168, v169
	v_cvt_pk_bf16_f32 v11, v170, v171
	v_cvt_pk_bf16_f32 v12, v172, v173
	v_cvt_pk_bf16_f32 v13, v174, v175
	global_store_dwordx4 v[70:71], v[10:13], off
	v_mul_f32_e32 v184, v184, v176
	v_mul_f32_e32 v185, v185, v177
	v_mul_f32_e32 v186, v186, v178
	v_mul_f32_e32 v187, v187, v179
	v_mul_f32_e32 v188, v188, v180
	v_mul_f32_e32 v189, v189, v181
	v_mul_f32_e32 v190, v190, v182
	v_mul_f32_e32 v191, v191, v183
	v_cvt_pk_bf16_f32 v14, v184, v185
	v_cvt_pk_bf16_f32 v15, v186, v187
	v_cvt_pk_bf16_f32 v16, v188, v189
	v_cvt_pk_bf16_f32 v17, v190, v191
	v_mul_f32_e32 v168, v168, v168
	v_mul_f32_e32 v169, v169, v169
	v_mul_f32_e32 v170, v170, v170
	v_mul_f32_e32 v171, v171, v171
	v_mul_f32_e32 v172, v172, v172
	v_mul_f32_e32 v173, v173, v173
	v_mul_f32_e32 v174, v174, v174
	v_mul_f32_e32 v175, v175, v175
	v_add_f32_e32 v168, v168, v169
	v_add_f32_e32 v170, v170, v171
	v_add_f32_e32 v168, v168, v170
	v_add_f32_e32 v172, v172, v173
	v_add_f32_e32 v168, v168, v172
	v_add_f32_e32 v174, v174, v175
	v_add_f32_e32 v168, v168, v174
	v_add_f32_e32 v2, v2, v168
	v_mfma_f32_16x16x32_bf16 v[6:9], v[10:13], v[14:17], v[6:9]
	s_waitcnt vmcnt(0)
	v_cvt_pk_bf16_f32 v18, v192, v193
	v_cvt_pk_bf16_f32 v19, v194, v195
	v_cvt_pk_bf16_f32 v20, v196, v197
	v_cvt_pk_bf16_f32 v21, v198, v199
	global_store_dwordx4 v[70:71], v[18:21], off offset:64
	v_mul_f32_e32 v208, v208, v200
	v_mul_f32_e32 v209, v209, v201
	v_mul_f32_e32 v210, v210, v202
	v_mul_f32_e32 v211, v211, v203
	v_mul_f32_e32 v212, v212, v204
	v_mul_f32_e32 v213, v213, v205
	v_mul_f32_e32 v214, v214, v206
	v_mul_f32_e32 v215, v215, v207
	v_cvt_pk_bf16_f32 v22, v208, v209
	v_cvt_pk_bf16_f32 v23, v210, v211
	v_cvt_pk_bf16_f32 v24, v212, v213
	v_cvt_pk_bf16_f32 v25, v214, v215
	v_mul_f32_e32 v192, v192, v192
	v_mul_f32_e32 v193, v193, v193
	v_mul_f32_e32 v194, v194, v194
	v_mul_f32_e32 v195, v195, v195
	v_mul_f32_e32 v196, v196, v196
	v_mul_f32_e32 v197, v197, v197
	v_mul_f32_e32 v198, v198, v198
	v_mul_f32_e32 v199, v199, v199
	v_add_f32_e32 v192, v192, v193
	v_add_f32_e32 v194, v194, v195
	v_add_f32_e32 v192, v192, v194
	v_add_f32_e32 v196, v196, v197
	v_add_f32_e32 v192, v192, v196
	v_add_f32_e32 v198, v198, v199
	v_add_f32_e32 v192, v192, v198
	v_add_f32_e32 v2, v2, v192
	v_mfma_f32_16x16x32_bf16 v[6:9], v[18:21], v[22:25], v[6:9]
	s_nop 7
	s_andn2_b64 vcc, exec, s[18:19]
	v_add_u32_e32 v12, 0x3000, v92
	v_add_u32_e32 v4, 0x3008, v92
	s_cbranch_vccnz .LBB0_13
	s_nop 2
	ds_write2_b32 v12, v6, v7 offset1:1
	ds_write2_b32 v4, v8, v9 offset1:1
	ds_write_b32 v92, v2 offset:12304
